# v42 + P5b row-stat exchange: acquire L2 invalidate dropped (the cross-workgroup reads that follow are sc1 loads)
# speedup vs baseline: 1.0059x; 1.0012x over previous
.LBB0_1533:
.LBB0_1534:
	s_waitcnt vmcnt(0) lgkmcnt(0)
	s_barrier
	s_and_saveexec_b64 s[50:51], s[22:23]
	s_cbranch_execz .LBB0_1536
	global_load_dword v152, v[142:143], off sc1
	global_load_dword v160, v[142:143], off offset:4 sc1
	global_load_dword v161, v[142:143], off offset:8 sc1
	s_nop 0
	global_load_dword v142, v[142:143], off offset:12 sc1
	v_lshl_add_u32 v136, v136, 2, 0
	v_add_u32_e32 v136, 0x21000, v136
	s_waitcnt vmcnt(0)
	v_add_f32_e32 v143, 0, v152
	v_add_f32_e32 v143, v143, v160
	v_add_f32_e32 v143, v143, v161
	v_add_f32_e32 v142, v143, v142
	v_fmamk_f32 v142, v142, 0x3a800000, v254
	v_rsq_f32_e32 v142, v142
	ds_write_b32 v136, v142
